# GLA pass1 vt tile load hoisted to unit start, issued together with kv load
# speedup vs baseline: 1.0400x; 1.0039x over previous
.LBB0_595:
	s_mul_hi_i32 s0, s8, 0x3e0f83e1
	s_lshr_b32 s1, s0, 31
	s_ashr_i32 s0, s0, 5
	s_add_i32 s0, s0, s1
	s_mul_i32 s1, s0, 0x84
	s_sub_i32 s20, s8, s1
	s_and_b32 s19, s0, 1
	s_bfe_u32 s21, s0, 0x20001
	s_lshl_b32 s1, s20, 6
	s_cmp_lt_i32 s20, 4
	s_cselect_b32 s9, s7, s6
	v_mov_b32_e32 v16, v207
	s_add_i32 s9, s9, s1
	v_mov_b32_e32 v10, v207
	s_cmp_eq_u32 s19, 0
	s_barrier
	s_cselect_b64 s[42:43], -1, 0
	v_ashrrev_i32_e32 v4, 3, v10
	v_lshlrev_b32_e32 v0, 4, v10
	s_cmp_eq_u32 s19, 1
	v_and_b32_e32 v2, 0x70, v0
	v_add_u32_e32 v3, s9, v4
	v_mov_b64_e32 v[0:1], s[36:37]
	s_cselect_b64 s[2:3], -1, 0
	s_and_b32 s22, s0, -8
	v_mad_i64_i32 v[0:1], s[0:1], v3, s14, v[0:1]
	s_lshl_b32 s26, s21, 8
	s_lshl_b32 s18, s21, 7
	v_lshl_add_u64 v[0:1], v[0:1], 0, s[26:27]
	v_lshlrev_b32_e32 v128, 1, v2
	v_lshlrev_b32_e32 v3, 9, v4
	v_lshlrev_b32_e32 v5, 2, v2
	v_lshl_add_u64 v[0:1], v[0:1], 0, v[128:129]
	s_mov_b64 s[0:1], -1
	s_movk_i32 s100, 0xe00
	s_cmp_eq_u32 s22, 8
	s_cselect_b32 s100, 0x400, s100
	s_lshl_b32 s101, s21, 7
	s_add_i32 s100, s100, s101
	s_lshl_b32 s100, s100, 1
	s_mov_b32 s101, 0
	v_and_b32_e32 v162, 63, v207
	v_or_b32_e32 v162, s9, v162
	v_mul_u32_u24_e32 v162, 0x1200, v162
	v_mov_b32_e32 v163, 0
	v_lshl_add_u64 v[162:163], v[162:163], 1, s[36:37]
	v_lshl_add_u64 v[162:163], v[162:163], 0, s[100:101]
	v_ashrrev_i32_e32 v164, 2, v207
	v_and_b32_e32 v164, -16, v164
	v_mov_b32_e32 v165, 0
	v_lshl_add_u64 v[162:163], v[164:165], 1, v[162:163]
	global_load_dwordx4 v[154:157], v[162:163], off
	global_load_dwordx4 v[158:161], v[162:163], off offset:16
	s_cmp_lg_u32 s22, 8
	v_add3_u32 v5, 0, v3, v5
	s_cbranch_scc0 .LBB0_613
	s_and_b64 s[0:1], s[42:43], exec
	s_cselect_b32 s26, s15, 0x1800
	v_lshl_add_u64 v[12:13], v[0:1], 0, s[26:27]
	global_load_dwordx4 v[6:9], v[12:13], off
	global_load_dwordx4 v[26:29], v[12:13], off offset:16
	v_or_b32_e32 v2, s18, v2
	v_lshlrev_b32_e32 v128, 2, v2
	v_lshl_add_u64 v[2:3], s[78:79], 0, v[128:129]
	s_waitcnt vmcnt(0) lgkmcnt(0)
	v_lshlrev_b32_e32 v11, 16, v6
	v_and_b32_e32 v25, 0xffff0000, v6
	global_load_dword v6, v[2:3], off
	v_lshlrev_b32_e32 v15, 16, v8
	v_and_b32_e32 v12, 0xffff0000, v8
	v_mul_f32_e32 v8, 0xbfb8aa3b, v11
	v_exp_f32_e32 v8, v8
	v_lshlrev_b32_e32 v20, 16, v9
	v_and_b32_e32 v17, 0xffff0000, v9
	v_lshlrev_b32_e32 v24, 16, v26
	v_add_f32_e32 v8, 1.0, v8
	v_rcp_f32_e32 v11, v8
	v_and_b32_e32 v21, 0xffff0000, v26
	v_lshlrev_b32_e32 v23, 16, v27
	v_and_b32_e32 v22, 0xffff0000, v27
	v_lshlrev_b32_e32 v19, 16, v28
	v_and_b32_e32 v18, 0xffff0000, v28
	v_mul_f32_e32 v8, 1.0, v11
	v_mul_f32_e32 v9, 0xbfb8aa3b, v25
	v_exp_f32_e32 v9, v9
	v_lshlrev_b32_e32 v30, 16, v7
	v_and_b32_e32 v31, 0xffff0000, v7
	v_lshlrev_b32_e32 v14, 16, v29
	v_add_f32_e32 v9, 1.0, v9
	v_rcp_f32_e32 v25, v9
	v_and_b32_e32 v13, 0xffff0000, v29
	v_mul_f32_e32 v15, 0xbfb8aa3b, v15
	v_exp_f32_e32 v15, v15
	v_mul_f32_e32 v9, 1.0, v25
	v_mul_f32_e32 v11, 0xbfb8aa3b, v30
	v_exp_f32_e32 v11, v11
	v_add_f32_e32 v15, 1.0, v15
	v_mul_f32_e32 v12, 0xbfb8aa3b, v12
	v_exp_f32_e32 v12, v12
	v_add_f32_e32 v11, 1.0, v11
	v_mul_f32_e32 v20, 0xbfb8aa3b, v20
	v_exp_f32_e32 v20, v20
	v_add_f32_e32 v12, 1.0, v12
	v_mul_f32_e32 v17, 0xbfb8aa3b, v17
	v_exp_f32_e32 v17, v17
	v_add_f32_e32 v20, 1.0, v20
	v_mul_f32_e32 v24, 0xbfb8aa3b, v24
	v_exp_f32_e32 v24, v24
	v_add_f32_e32 v17, 1.0, v17
	v_mul_f32_e32 v21, 0xbfb8aa3b, v21
	v_exp_f32_e32 v21, v21
	v_add_f32_e32 v24, 1.0, v24
	v_mul_f32_e32 v23, 0xbfb8aa3b, v23
	v_exp_f32_e32 v23, v23
	v_add_f32_e32 v21, 1.0, v21
	v_mul_f32_e32 v22, 0xbfb8aa3b, v22
	v_exp_f32_e32 v22, v22
	v_add_f32_e32 v23, 1.0, v23
	v_mul_f32_e32 v19, 0xbfb8aa3b, v19
	v_exp_f32_e32 v19, v19
	v_add_f32_e32 v22, 1.0, v22
	v_mul_f32_e32 v18, 0xbfb8aa3b, v18
	v_exp_f32_e32 v18, v18
	v_add_f32_e32 v19, 1.0, v19
	v_mul_f32_e32 v14, 0xbfb8aa3b, v14
	s_waitcnt vmcnt(0) lgkmcnt(0)
	v_sub_f32_e32 v7, 1.0, v6
	v_fmac_f32_e32 v6, v7, v8
	v_cmp_gt_f32_e32 vcc, s12, v6
	v_add_f32_e32 v18, 1.0, v18
	v_exp_f32_e32 v14, v14
	v_cndmask_b32_e64 v7, 0, 32, vcc
	v_ldexp_f32 v7, v6, v7
	v_log_f32_e32 v7, v7
	v_add_f32_e32 v14, 1.0, v14
	v_mul_f32_e32 v13, 0xbfb8aa3b, v13
	v_exp_f32_e32 v13, v13
	v_mul_f32_e32 v8, 0x3f317217, v7
	v_fma_f32 v8, v7, s86, -v8
	v_fmac_f32_e32 v8, 0x3377d1cf, v7
	v_fmac_f32_e32 v8, 0x3f317217, v7
	v_cmp_lt_f32_e64 s[0:1], |v7|, s87
	v_add_f32_e32 v13, 1.0, v13
	s_nop 0
	v_cndmask_b32_e64 v7, v7, v8, s[0:1]
	v_cndmask_b32_e32 v8, 0, v231, vcc
	v_sub_f32_e32 v7, v7, v8
	ds_write_b32 v5, v7
	global_load_dword v7, v[2:3], off offset:4
	s_waitcnt vmcnt(0) lgkmcnt(0)
	v_sub_f32_e32 v8, 1.0, v7
	v_fmac_f32_e32 v7, v8, v9
	v_cmp_gt_f32_e32 vcc, s12, v7
	s_nop 1
	v_cndmask_b32_e64 v8, 0, 32, vcc
	v_ldexp_f32 v8, v7, v8
	v_log_f32_e32 v8, v8
	s_nop 0
	v_mul_f32_e32 v9, 0x3f317217, v8
	v_fma_f32 v9, v8, s86, -v9
	v_fmac_f32_e32 v9, 0x3377d1cf, v8
	v_fmac_f32_e32 v9, 0x3f317217, v8
	v_cmp_lt_f32_e64 s[0:1], |v8|, s87
	s_nop 1
	v_cndmask_b32_e64 v8, v8, v9, s[0:1]
	v_cndmask_b32_e32 v9, 0, v231, vcc
	v_sub_f32_e32 v8, v8, v9
	ds_write_b32 v5, v8 offset:4
	global_load_dword v8, v[2:3], off offset:8
	v_rcp_f32_e32 v26, v11
	s_waitcnt vmcnt(0) lgkmcnt(0)
	v_sub_f32_e32 v9, 1.0, v8
	v_mul_f32_e32 v11, 1.0, v26
	v_mul_f32_e32 v25, 0xbfb8aa3b, v31
	v_exp_f32_e32 v25, v25
	v_fmac_f32_e32 v8, v11, v9
	v_add_f32_e32 v25, 1.0, v25
	v_rcp_f32_e32 v27, v25
	s_nop 0
	v_cmp_gt_f32_e32 vcc, s12, v8
	v_mul_f32_e32 v25, 1.0, v27
	s_nop 0
	v_cndmask_b32_e64 v9, 0, 32, vcc
	v_ldexp_f32 v9, v8, v9
	v_log_f32_e32 v9, v9
	s_nop 0
	v_mul_f32_e32 v11, 0x3f317217, v9
	v_fma_f32 v11, v9, s86, -v11
	v_fmac_f32_e32 v11, 0x3377d1cf, v9
	v_fmac_f32_e32 v11, 0x3f317217, v9
	v_cmp_lt_f32_e64 s[0:1], |v9|, s87
	s_nop 1
	v_cndmask_b32_e64 v9, v9, v11, s[0:1]
	v_cndmask_b32_e32 v11, 0, v231, vcc
	v_sub_f32_e32 v9, v9, v11
	ds_write_b32 v5, v9 offset:8
	global_load_dword v9, v[2:3], off offset:12
	s_waitcnt vmcnt(0) lgkmcnt(0)
	v_sub_f32_e32 v11, 1.0, v9
	v_fmac_f32_e32 v9, v25, v11
	v_cmp_gt_f32_e32 vcc, s12, v9
	s_nop 1
	v_cndmask_b32_e64 v11, 0, 32, vcc
	v_ldexp_f32 v11, v9, v11
	v_log_f32_e32 v11, v11
	s_nop 0
	v_mul_f32_e32 v25, 0x3f317217, v11
	v_fma_f32 v25, v11, s86, -v25
	v_fmac_f32_e32 v25, 0x3377d1cf, v11
	v_fmac_f32_e32 v25, 0x3f317217, v11
	v_cmp_lt_f32_e64 s[0:1], |v11|, s87
	s_nop 1
	v_cndmask_b32_e64 v11, v11, v25, s[0:1]
	v_cndmask_b32_e32 v25, 0, v231, vcc
	v_sub_f32_e32 v11, v11, v25
	ds_write_b32 v5, v11 offset:12
	global_load_dword v11, v[2:3], off offset:16
	v_rcp_f32_e32 v27, v15
	s_waitcnt vmcnt(0) lgkmcnt(0)
	v_sub_f32_e32 v25, 1.0, v11
	v_mul_f32_e32 v15, 1.0, v27
	v_rcp_f32_e32 v27, v12
	v_fmac_f32_e32 v11, v15, v25
	v_cmp_gt_f32_e32 vcc, s12, v11
	v_mul_f32_e32 v26, 1.0, v27
	s_nop 0
	v_cndmask_b32_e64 v12, 0, 32, vcc
	v_ldexp_f32 v12, v11, v12
	v_log_f32_e32 v12, v12
	s_nop 0
	v_mul_f32_e32 v15, 0x3f317217, v12
	v_fma_f32 v15, v12, s86, -v15
	v_fmac_f32_e32 v15, 0x3377d1cf, v12
	v_fmac_f32_e32 v15, 0x3f317217, v12
	v_cmp_lt_f32_e64 s[0:1], |v12|, s87
	s_nop 1
	v_cndmask_b32_e64 v12, v12, v15, s[0:1]
	v_cndmask_b32_e32 v15, 0, v231, vcc
	v_sub_f32_e32 v12, v12, v15
	ds_write_b32 v5, v12 offset:16
	global_load_dword v12, v[2:3], off offset:20
	s_waitcnt vmcnt(0) lgkmcnt(0)
	v_sub_f32_e32 v15, 1.0, v12
	v_fmac_f32_e32 v12, v26, v15
	v_cmp_gt_f32_e32 vcc, s12, v12
	s_nop 1
	v_cndmask_b32_e64 v15, 0, 32, vcc
	v_ldexp_f32 v15, v12, v15
	v_log_f32_e32 v15, v15
	s_nop 0
	v_mul_f32_e32 v25, 0x3f317217, v15
	v_fma_f32 v25, v15, s86, -v25
	v_fmac_f32_e32 v25, 0x3377d1cf, v15
	v_fmac_f32_e32 v25, 0x3f317217, v15
	v_cmp_lt_f32_e64 s[0:1], |v15|, s87
	s_nop 1
	v_cndmask_b32_e64 v15, v15, v25, s[0:1]
	v_cndmask_b32_e32 v25, 0, v231, vcc
	v_sub_f32_e32 v15, v15, v25
	ds_write_b32 v5, v15 offset:20
	global_load_dword v15, v[2:3], off offset:24
	v_rcp_f32_e32 v27, v20
	s_waitcnt vmcnt(0) lgkmcnt(0)
	v_sub_f32_e32 v25, 1.0, v15
	v_mul_f32_e32 v20, 1.0, v27
	v_rcp_f32_e32 v27, v17
	v_fmac_f32_e32 v15, v20, v25
	v_cmp_gt_f32_e32 vcc, s12, v15
	v_mul_f32_e32 v26, 1.0, v27
	s_nop 0
	v_cndmask_b32_e64 v17, 0, 32, vcc
	v_ldexp_f32 v17, v15, v17
	v_log_f32_e32 v17, v17
	s_nop 0
	v_mul_f32_e32 v20, 0x3f317217, v17
	v_fma_f32 v20, v17, s86, -v20
	v_fmac_f32_e32 v20, 0x3377d1cf, v17
	v_fmac_f32_e32 v20, 0x3f317217, v17
	v_cmp_lt_f32_e64 s[0:1], |v17|, s87
	s_nop 1
	v_cndmask_b32_e64 v17, v17, v20, s[0:1]
	v_cndmask_b32_e32 v20, 0, v231, vcc
	v_sub_f32_e32 v17, v17, v20
	ds_write_b32 v5, v17 offset:24
	global_load_dword v17, v[2:3], off offset:28
	s_waitcnt vmcnt(0) lgkmcnt(0)
	v_sub_f32_e32 v20, 1.0, v17
	v_fmac_f32_e32 v17, v26, v20
	v_cmp_gt_f32_e32 vcc, s12, v17
	s_nop 1
	v_cndmask_b32_e64 v20, 0, 32, vcc
	v_ldexp_f32 v20, v17, v20
	v_log_f32_e32 v20, v20
	s_nop 0
	v_mul_f32_e32 v25, 0x3f317217, v20
	v_fma_f32 v25, v20, s86, -v25
	v_fmac_f32_e32 v25, 0x3377d1cf, v20
	v_fmac_f32_e32 v25, 0x3f317217, v20
	v_cmp_lt_f32_e64 s[0:1], |v20|, s87
	s_nop 1
	v_cndmask_b32_e64 v20, v20, v25, s[0:1]
	v_cndmask_b32_e32 v25, 0, v231, vcc
	v_sub_f32_e32 v20, v20, v25
	ds_write_b32 v5, v20 offset:28
	global_load_dword v20, v[2:3], off offset:32
	v_rcp_f32_e32 v27, v24
	s_waitcnt vmcnt(0) lgkmcnt(0)
	v_sub_f32_e32 v25, 1.0, v20
	v_mul_f32_e32 v24, 1.0, v27
	v_rcp_f32_e32 v27, v21
	v_fmac_f32_e32 v20, v24, v25
	v_cmp_gt_f32_e32 vcc, s12, v20
	v_mul_f32_e32 v26, 1.0, v27
	s_nop 0
	v_cndmask_b32_e64 v21, 0, 32, vcc
	v_ldexp_f32 v21, v20, v21
	v_log_f32_e32 v21, v21
	s_nop 0
	v_mul_f32_e32 v24, 0x3f317217, v21
	v_fma_f32 v24, v21, s86, -v24
	v_fmac_f32_e32 v24, 0x3377d1cf, v21
	v_fmac_f32_e32 v24, 0x3f317217, v21
	v_cmp_lt_f32_e64 s[0:1], |v21|, s87
	s_nop 1
	v_cndmask_b32_e64 v21, v21, v24, s[0:1]
	v_cndmask_b32_e32 v24, 0, v231, vcc
	v_sub_f32_e32 v21, v21, v24
	ds_write_b32 v5, v21 offset:32
	global_load_dword v21, v[2:3], off offset:36
	s_waitcnt vmcnt(0) lgkmcnt(0)
	v_sub_f32_e32 v24, 1.0, v21
	v_fmac_f32_e32 v21, v26, v24
	v_cmp_gt_f32_e32 vcc, s12, v21
	s_nop 1
	v_cndmask_b32_e64 v24, 0, 32, vcc
	v_ldexp_f32 v24, v21, v24
	v_log_f32_e32 v24, v24
	s_nop 0
	v_mul_f32_e32 v25, 0x3f317217, v24
	v_fma_f32 v25, v24, s86, -v25
	v_fmac_f32_e32 v25, 0x3377d1cf, v24
	v_fmac_f32_e32 v25, 0x3f317217, v24
	v_cmp_lt_f32_e64 s[0:1], |v24|, s87
	s_nop 1
	v_cndmask_b32_e64 v24, v24, v25, s[0:1]
	v_cndmask_b32_e32 v25, 0, v231, vcc
	v_sub_f32_e32 v24, v24, v25
	ds_write_b32 v5, v24 offset:36
	global_load_dword v24, v[2:3], off offset:40
	v_rcp_f32_e32 v27, v23
	s_waitcnt vmcnt(0) lgkmcnt(0)
	v_sub_f32_e32 v25, 1.0, v24
	v_mul_f32_e32 v23, 1.0, v27
	v_rcp_f32_e32 v27, v22
	v_fmac_f32_e32 v24, v23, v25
	v_cmp_gt_f32_e32 vcc, s12, v24
	v_mul_f32_e32 v26, 1.0, v27
	s_nop 0
	v_cndmask_b32_e64 v22, 0, 32, vcc
	v_ldexp_f32 v22, v24, v22
	v_log_f32_e32 v22, v22
	s_nop 0
	v_mul_f32_e32 v23, 0x3f317217, v22
	v_fma_f32 v23, v22, s86, -v23
	v_fmac_f32_e32 v23, 0x3377d1cf, v22
	v_fmac_f32_e32 v23, 0x3f317217, v22
	v_cmp_lt_f32_e64 s[0:1], |v22|, s87
	s_nop 1
	v_cndmask_b32_e64 v22, v22, v23, s[0:1]
	v_cndmask_b32_e32 v23, 0, v231, vcc
	v_sub_f32_e32 v22, v22, v23
	ds_write_b32 v5, v22 offset:40
	global_load_dword v22, v[2:3], off offset:44
	s_waitcnt vmcnt(0) lgkmcnt(0)
	v_sub_f32_e32 v23, 1.0, v22
	v_fmac_f32_e32 v22, v26, v23
	v_cmp_gt_f32_e32 vcc, s12, v22
	s_nop 1
	v_cndmask_b32_e64 v23, 0, 32, vcc
	v_ldexp_f32 v23, v22, v23
	v_log_f32_e32 v23, v23
	s_nop 0
	v_mul_f32_e32 v25, 0x3f317217, v23
	v_fma_f32 v25, v23, s86, -v25
	v_fmac_f32_e32 v25, 0x3377d1cf, v23
	v_fmac_f32_e32 v25, 0x3f317217, v23
	v_cmp_lt_f32_e64 s[0:1], |v23|, s87
	s_nop 1
	v_cndmask_b32_e64 v23, v23, v25, s[0:1]
	v_cndmask_b32_e32 v25, 0, v231, vcc
	v_sub_f32_e32 v23, v23, v25
	ds_write_b32 v5, v23 offset:44
	global_load_dword v23, v[2:3], off offset:48
	v_rcp_f32_e32 v27, v19
	s_waitcnt vmcnt(0) lgkmcnt(0)
	v_sub_f32_e32 v25, 1.0, v23
	v_mul_f32_e32 v19, 1.0, v27
	v_rcp_f32_e32 v27, v18
	v_fmac_f32_e32 v23, v19, v25
	v_cmp_gt_f32_e32 vcc, s12, v23
	v_mul_f32_e32 v26, 1.0, v27
	s_nop 0
	v_cndmask_b32_e64 v18, 0, 32, vcc
	v_ldexp_f32 v18, v23, v18
	v_log_f32_e32 v18, v18
	s_nop 0
	v_mul_f32_e32 v19, 0x3f317217, v18
	v_fma_f32 v19, v18, s86, -v19
	v_fmac_f32_e32 v19, 0x3377d1cf, v18
	v_fmac_f32_e32 v19, 0x3f317217, v18
	v_cmp_lt_f32_e64 s[0:1], |v18|, s87
	s_nop 1
	v_cndmask_b32_e64 v18, v18, v19, s[0:1]
	v_cndmask_b32_e32 v19, 0, v231, vcc
	v_sub_f32_e32 v18, v18, v19
	ds_write_b32 v5, v18 offset:48
	global_load_dword v18, v[2:3], off offset:52
	s_waitcnt vmcnt(0) lgkmcnt(0)
	v_sub_f32_e32 v19, 1.0, v18
	v_fmac_f32_e32 v18, v26, v19
	v_cmp_gt_f32_e32 vcc, s12, v18
	s_nop 1
	v_cndmask_b32_e64 v19, 0, 32, vcc
	v_ldexp_f32 v19, v18, v19
	v_log_f32_e32 v19, v19
	s_nop 0
	v_mul_f32_e32 v25, 0x3f317217, v19
	v_fma_f32 v25, v19, s86, -v25
	v_fmac_f32_e32 v25, 0x3377d1cf, v19
	v_fmac_f32_e32 v25, 0x3f317217, v19
	v_cmp_lt_f32_e64 s[0:1], |v19|, s87
	s_nop 1
	v_cndmask_b32_e64 v19, v19, v25, s[0:1]
	v_cndmask_b32_e32 v25, 0, v231, vcc
	v_sub_f32_e32 v19, v19, v25
	ds_write_b32 v5, v19 offset:52
	global_load_dword v25, v[2:3], off offset:56
	v_rcp_f32_e32 v27, v14
	s_waitcnt vmcnt(0) lgkmcnt(0)
	v_sub_f32_e32 v19, 1.0, v25
	v_mul_f32_e32 v14, 1.0, v27
	v_rcp_f32_e32 v27, v13
	v_fmac_f32_e32 v25, v14, v19
	v_cmp_gt_f32_e32 vcc, s12, v25
	v_mul_f32_e32 v13, 1.0, v27
	s_nop 0
	v_cndmask_b32_e64 v14, 0, 32, vcc
	v_ldexp_f32 v14, v25, v14
	v_log_f32_e32 v14, v14
	s_nop 0
	v_mul_f32_e32 v19, 0x3f317217, v14
	v_fma_f32 v19, v14, s86, -v19
	v_fmac_f32_e32 v19, 0x3377d1cf, v14
	v_fmac_f32_e32 v19, 0x3f317217, v14
	v_cmp_lt_f32_e64 s[0:1], |v14|, s87
	s_nop 1
	v_cndmask_b32_e64 v14, v14, v19, s[0:1]
	v_cndmask_b32_e32 v19, 0, v231, vcc
	v_sub_f32_e32 v14, v14, v19
	ds_write_b32 v5, v14 offset:56
	global_load_dword v3, v[2:3], off offset:60
	s_waitcnt vmcnt(0) lgkmcnt(0)
	v_sub_f32_e32 v2, 1.0, v3
	v_fmac_f32_e32 v3, v13, v2
	v_cmp_gt_f32_e32 vcc, s12, v3
	s_nop 1
	v_cndmask_b32_e64 v2, 0, 32, vcc
	v_ldexp_f32 v2, v3, v2
	v_log_f32_e32 v2, v2
	s_nop 0
	v_mul_f32_e32 v13, 0x3f317217, v2
	v_fma_f32 v13, v2, s86, -v13
	v_fmac_f32_e32 v13, 0x3377d1cf, v2
	v_fmac_f32_e32 v13, 0x3f317217, v2
	v_cmp_lt_f32_e64 s[0:1], |v2|, s87
	s_nop 1
	v_cndmask_b32_e64 v2, v2, v13, s[0:1]
	v_cndmask_b32_e32 v13, 0, v231, vcc
	v_sub_f32_e32 v2, v2, v13
	v_ashrrev_i32_e32 v13, 7, v10
	v_and_b32_e32 v10, 0x7f, v10
	v_lshlrev_b32_e32 v14, 13, v13
	v_lshlrev_b32_e32 v19, 2, v10
	ds_write_b32 v5, v2 offset:60
	v_add3_u32 v2, 0, v19, v14
	s_mov_b64 s[0:1], -1
	s_and_b64 vcc, exec, s[2:3]
	s_waitcnt lgkmcnt(0)
	s_barrier
	s_cbranch_vccz .LBB0_598
	ds_read2st64_b32 v[26:27], v2 offset0:28 offset1:30
	s_mov_b64 s[0:1], 0
	s_waitcnt lgkmcnt(0)
	v_add_f32_e32 v27, 0, v27
	v_add_f32_e32 v28, v27, v26
	ds_write2st64_b32 v2, v28, v27 offset0:28 offset1:30
	ds_read2st64_b32 v[26:27], v2 offset0:24 offset1:26
	s_waitcnt lgkmcnt(0)
	v_add_f32_e32 v27, v28, v27
	v_add_f32_e32 v28, v27, v26
	ds_write2st64_b32 v2, v28, v27 offset0:24 offset1:26
	ds_read2st64_b32 v[26:27], v2 offset0:20 offset1:22
	s_waitcnt lgkmcnt(0)
	v_add_f32_e32 v27, v28, v27
	v_add_f32_e32 v28, v27, v26
	ds_write2st64_b32 v2, v28, v27 offset0:20 offset1:22
	ds_read2st64_b32 v[26:27], v2 offset0:16 offset1:18
	s_waitcnt lgkmcnt(0)
	v_add_f32_e32 v27, v28, v27
	v_add_f32_e32 v28, v27, v26
	ds_write2st64_b32 v2, v28, v27 offset0:16 offset1:18
	ds_read2st64_b32 v[26:27], v2 offset0:12 offset1:14
	s_waitcnt lgkmcnt(0)
	v_add_f32_e32 v27, v28, v27
	v_add_f32_e32 v28, v27, v26
	ds_write2st64_b32 v2, v28, v27 offset0:12 offset1:14
	ds_read2st64_b32 v[26:27], v2 offset0:8 offset1:10
	s_waitcnt lgkmcnt(0)
	v_add_f32_e32 v27, v28, v27
	v_add_f32_e32 v28, v27, v26
	ds_write2st64_b32 v2, v28, v27 offset0:8 offset1:10
	ds_read2st64_b32 v[26:27], v2 offset0:4 offset1:6
	s_waitcnt lgkmcnt(0)
	v_add_f32_e32 v27, v28, v27
	v_add_f32_e32 v28, v27, v26
	ds_write2st64_b32 v2, v28, v27 offset0:4 offset1:6
	ds_read2st64_b32 v[26:27], v2 offset1:2
	s_waitcnt lgkmcnt(0)
	v_add_f32_e32 v27, v28, v27
	v_add_f32_e32 v26, v27, v26
	ds_write2st64_b32 v2, v26, v27 offset1:2

.LBB0_615:
	s_cmp_gt_i32 s20, 3
	s_cselect_b32 s0, 0x87, 3
	s_sub_i32 s3, s0, s20
	s_and_b64 s[0:1], s[42:43], exec
	s_cselect_b32 s0, s20, s3
	s_lshl_b32 s1, s21, 1
	s_sub_i32 s3, s19, s22
	s_add_i32 s1, s3, s1
	v_lshlrev_b32_e32 v0, 4, v16
	s_add_i32 s1, s1, 8
	v_and_b32_e32 v23, 0x70, v0
	s_mul_hi_u32 s3, s1, 0x84
	s_mulk_i32 s1, 0x84
	s_ashr_i32 s19, s0, 31
	v_mov_b32_e32 v0, v207
	s_add_u32 s0, s1, s0
	s_addc_u32 s1, s3, s19
	v_and_b32_e32 v6, 63, v0
	v_or_b32_e32 v1, s9, v6
	s_movk_i32 s3, 0x1200
	v_mul_lo_u32 v128, v1, s3
	v_ashrrev_i32_e32 v0, 2, v0
	v_lshl_add_u64 v[2:3], v[128:129], 1, s[36:37]
	s_lshl_b32 s26, s2, 1
	v_and_b32_e32 v0, -16, v0
	v_lshl_add_u64 v[2:3], v[2:3], 0, s[26:27]
	s_lshl_b32 s26, s18, 1
	v_lshl_add_u64 v[2:3], v[2:3], 0, s[26:27]
	v_ashrrev_i32_e32 v1, 31, v0
	v_lshl_add_u64 v[4:5], v[0:1], 1, v[2:3]
	s_movk_i32 s2, 0x90
	v_lshlrev_b32_e32 v9, 1, v6
	v_mul_lo_u32 v10, v0, s2
	v_readlane_b32 s2, v252, 12
	v_ashrrev_i32_e32 v8, 3, v16
	v_lshlrev_b32_e32 v44, 1, v8
	v_add3_u32 v11, s2, v9, v10
	v_add3_u32 v9, s2, v10, v9
	s_and_b64 s[2:3], s[42:43], exec
	s_cselect_b32 s2, 0x7e00, 0
	s_add_i32 s9, s2, 0
	v_readlane_b32 s2, v251, 5
	s_waitcnt vmcnt(0) lgkmcnt(0)
	ds_write_b16 v11, v154
	ds_write_b16_d16_hi v9, v154 offset:144
	ds_write_b16 v11, v155 offset:288
	ds_write_b16_d16_hi v9, v155 offset:432
	ds_write_b16 v11, v156 offset:576
	ds_write_b16_d16_hi v9, v156 offset:720
	ds_write_b16 v11, v157 offset:864
	ds_write_b16_d16_hi v9, v157 offset:1008
	ds_write_b16 v11, v158 offset:1152
	ds_write_b16_d16_hi v9, v158 offset:1296
	ds_write_b16 v11, v159 offset:1440
	ds_write_b16_d16_hi v9, v159 offset:1584
	ds_write_b16 v11, v160 offset:1728
	ds_write_b16_d16_hi v9, v160 offset:1872
	ds_write_b16 v11, v161 offset:2016
	ds_write_b16_d16_hi v9, v161 offset:2160
	v_lshlrev_b32_e32 v0, 2, v23
	v_add_u32_e32 v22, s9, v0
	v_lshlrev_b32_e32 v1, 9, v8
	v_add3_u32 v25, 0, v1, v0
	ds_read_b128 v[36:39], v22
	ds_read_b128 v[8:11], v22 offset:16
	ds_read_b128 v[0:3], v22 offset:32
	ds_read_b128 v[40:43], v25
	ds_read_b128 v[12:15], v25 offset:16
	ds_read_b128 v[4:7], v25 offset:32
	v_mul_u32_u24_e32 v23, 0x90, v23
	v_add3_u32 v23, s2, v44, v23
	s_waitcnt lgkmcnt(2)
	v_sub_f32_e32 v36, v36, v40
	s_waitcnt lgkmcnt(1)
	v_sub_f32_e32 v8, v8, v12
	s_waitcnt lgkmcnt(0)
	v_sub_f32_e32 v0, v0, v4
	v_mul_f32_e32 v36, 0x3fb8aa3b, v36
	v_mul_f32_e32 v8, 0x3fb8aa3b, v8
	v_mul_f32_e32 v0, 0x3fb8aa3b, v0
	v_exp_f32_e32 v36, v36
	v_exp_f32_e32 v8, v8
	v_exp_f32_e32 v0, v0
	s_movk_i32 s2, 0x80
	v_mul_f32_e32 v35, v35, v36
	v_mul_f32_e32 v8, v31, v8
	v_mul_f32_e32 v0, v27, v0
	v_cvt_pk_bf16_f32 v35, v35, s0
	v_cvt_pk_bf16_f32 v8, v8, s0
	v_cvt_pk_bf16_f32 v0, v0, s0
	ds_write_b16 v23, v35
	v_sub_f32_e32 v35, v37, v41
	ds_write_b16 v23, v8 offset:576
	v_sub_f32_e32 v8, v9, v13
	ds_write_b16 v23, v0 offset:1152
	v_sub_f32_e32 v0, v1, v5
	v_mul_f32_e32 v35, 0x3fb8aa3b, v35
	v_mul_f32_e32 v8, 0x3fb8aa3b, v8
	v_mul_f32_e32 v0, 0x3fb8aa3b, v0
	v_exp_f32_e32 v35, v35
	v_exp_f32_e32 v8, v8
	v_exp_f32_e32 v0, v0
	v_cmp_gt_i32_e32 vcc, s2, v16
	v_mul_f32_e32 v34, v34, v35
	v_mul_f32_e32 v8, v30, v8
	v_mul_f32_e32 v0, v26, v0
	v_cvt_pk_bf16_f32 v34, v34, s0
	v_cvt_pk_bf16_f32 v8, v8, s0
	v_cvt_pk_bf16_f32 v0, v0, s0
	ds_write_b16 v23, v34 offset:144
	v_sub_f32_e32 v34, v38, v42
	ds_write_b16 v23, v8 offset:720
	v_sub_f32_e32 v8, v10, v14
	ds_write_b16 v23, v0 offset:1296
	v_sub_f32_e32 v0, v2, v6
	v_mul_f32_e32 v34, 0x3fb8aa3b, v34
	v_mul_f32_e32 v8, 0x3fb8aa3b, v8
	v_mul_f32_e32 v0, 0x3fb8aa3b, v0
	v_exp_f32_e32 v34, v34
	v_exp_f32_e32 v8, v8
	v_exp_f32_e32 v0, v0
	v_mul_f32_e32 v33, v33, v34
	v_mul_f32_e32 v8, v29, v8
	v_mul_f32_e32 v0, v24, v0
	v_cvt_pk_bf16_f32 v33, v33, s0
	v_cvt_pk_bf16_f32 v8, v8, s0
	v_cvt_pk_bf16_f32 v0, v0, s0
	ds_write_b16 v23, v33 offset:288
	v_sub_f32_e32 v33, v39, v43
	ds_write_b16 v23, v8 offset:864
	v_sub_f32_e32 v8, v11, v15
	ds_write_b16 v23, v0 offset:1440
	v_sub_f32_e32 v0, v3, v7
	v_mul_f32_e32 v33, 0x3fb8aa3b, v33
	v_mul_f32_e32 v8, 0x3fb8aa3b, v8
	v_mul_f32_e32 v0, 0x3fb8aa3b, v0
	v_exp_f32_e32 v33, v33
	v_exp_f32_e32 v8, v8
	v_exp_f32_e32 v0, v0
	v_mul_f32_e32 v32, v32, v33
	v_mul_f32_e32 v8, v28, v8
	v_mul_f32_e32 v0, v21, v0
	v_cvt_pk_bf16_f32 v32, v32, s0
	v_cvt_pk_bf16_f32 v8, v8, s0
	v_cvt_pk_bf16_f32 v0, v0, s0
	ds_write_b16 v23, v32 offset:432
	ds_write_b16 v23, v8 offset:1008
	ds_write_b16 v23, v0 offset:1584
	ds_read_b128 v[0:3], v22 offset:48
	ds_read_b128 v[4:7], v25 offset:48
	s_waitcnt lgkmcnt(0)
	v_sub_f32_e32 v0, v0, v4
	v_mul_f32_e32 v0, 0x3fb8aa3b, v0
	v_exp_f32_e32 v0, v0
	s_nop 0
	v_mul_f32_e32 v0, v20, v0
	v_cvt_pk_bf16_f32 v0, v0, s0
	ds_write_b16 v23, v0 offset:1728
	v_sub_f32_e32 v0, v1, v5
	v_mul_f32_e32 v0, 0x3fb8aa3b, v0
	v_exp_f32_e32 v0, v0
	s_nop 0
	v_mul_f32_e32 v0, v19, v0
	v_cvt_pk_bf16_f32 v0, v0, s0
	ds_write_b16 v23, v0 offset:1872
	v_sub_f32_e32 v0, v2, v6
	v_mul_f32_e32 v0, 0x3fb8aa3b, v0
	v_exp_f32_e32 v0, v0
	s_nop 0
	v_mul_f32_e32 v0, v18, v0
	v_cvt_pk_bf16_f32 v0, v0, s0
	ds_write_b16 v23, v0 offset:2016
	v_sub_f32_e32 v0, v3, v7
	v_mul_f32_e32 v0, 0x3fb8aa3b, v0
	v_exp_f32_e32 v0, v0
	s_nop 0
	v_mul_f32_e32 v0, v17, v0
	v_cvt_pk_bf16_f32 v0, v0, s0
	ds_write_b16 v23, v0 offset:2160
	s_and_saveexec_b64 s[2:3], vcc
	s_cbranch_execz .LBB0_594
	v_lshl_add_u32 v0, v16, 2, s9
	ds_read_b32 v0, v0
	s_lshl_b64 s[18:19], s[0:1], 9
	s_add_u32 s18, s90, s18
	s_addc_u32 s19, s91, s19
	v_ashrrev_i32_e32 v17, 31, v16
	s_waitcnt lgkmcnt(0)
	v_mul_f32_e32 v0, 0x3fb8aa3b, v0
	v_exp_f32_e32 v2, v0
	v_lshl_add_u64 v[0:1], v[16:17], 2, s[18:19]
	global_store_dword v[0:1], v2, off
	s_branch .LBB0_594

	.amdhsa_kernel _Z14fwd_megakernel6Params
		.amdhsa_group_segment_fixed_size 0
		.amdhsa_private_segment_fixed_size 0
		.amdhsa_kernarg_size 528
		.amdhsa_user_sgpr_count 2
		.amdhsa_user_sgpr_dispatch_ptr 0
		.amdhsa_user_sgpr_queue_ptr 0
		.amdhsa_user_sgpr_kernarg_segment_ptr 1
		.amdhsa_user_sgpr_dispatch_id 0
		.amdhsa_user_sgpr_kernarg_preload_length 0
		.amdhsa_user_sgpr_kernarg_preload_offset 0
		.amdhsa_user_sgpr_private_segment_size 0
		.amdhsa_uses_dynamic_stack 0
		.amdhsa_enable_private_segment 0
		.amdhsa_system_sgpr_workgroup_id_x 1
		.amdhsa_system_sgpr_workgroup_id_y 0
		.amdhsa_system_sgpr_workgroup_id_z 0
		.amdhsa_system_sgpr_workgroup_info 0
		.amdhsa_system_vgpr_workitem_id 2
		.amdhsa_next_free_vgpr 256
		.amdhsa_next_free_sgpr 102
		.amdhsa_accum_offset 256
		.amdhsa_reserve_vcc 1
		.amdhsa_float_round_mode_32 0
		.amdhsa_float_round_mode_16_64 0
		.amdhsa_float_denorm_mode_32 3
		.amdhsa_float_denorm_mode_16_64 3
		.amdhsa_dx10_clamp 1
		.amdhsa_ieee_mode 1
		.amdhsa_fp16_overflow 0
		.amdhsa_tg_split 0
		.amdhsa_exception_fp_ieee_invalid_op 0
		.amdhsa_exception_fp_denorm_src 0
		.amdhsa_exception_fp_ieee_div_zero 0
		.amdhsa_exception_fp_ieee_overflow 0
		.amdhsa_exception_fp_ieee_underflow 0
		.amdhsa_exception_fp_ieee_inexact 0
		.amdhsa_exception_int_div_zero 0
	.end_amdhsa_kernel

amdhsa.kernels:
  - .agpr_count:     0
    .args:
      - .offset:         0
        .size:           272
        .value_kind:     by_value
      - .offset:         272
        .size:           4
        .value_kind:     hidden_block_count_x
      - .offset:         276
        .size:           4
        .value_kind:     hidden_block_count_y
      - .offset:         280
        .size:           4
        .value_kind:     hidden_block_count_z
      - .offset:         284
        .size:           2
        .value_kind:     hidden_group_size_x
      - .offset:         286
        .size:           2
        .value_kind:     hidden_group_size_y
      - .offset:         288
        .size:           2
        .value_kind:     hidden_group_size_z
      - .offset:         290
        .size:           2
        .value_kind:     hidden_remainder_x
      - .offset:         292
        .size:           2
        .value_kind:     hidden_remainder_y
      - .offset:         294
        .size:           2
        .value_kind:     hidden_remainder_z
      - .offset:         312
        .size:           8
        .value_kind:     hidden_global_offset_x
      - .offset:         320
        .size:           8
        .value_kind:     hidden_global_offset_y
      - .offset:         328
        .size:           8
        .value_kind:     hidden_global_offset_z
      - .offset:         336
        .size:           2
        .value_kind:     hidden_grid_dims
      - .offset:         360
        .size:           8
        .value_kind:     hidden_multigrid_sync_arg
      - .offset:         392
        .size:           4
        .value_kind:     hidden_dynamic_lds_size
    .group_segment_fixed_size: 0
    .kernarg_segment_align: 8
    .kernarg_segment_size: 528
    .language:       OpenCL C
    .language_version:
      - 2
      - 0
    .max_flat_workgroup_size: 512
    .name:           _Z14fwd_megakernel6Params
    .private_segment_fixed_size: 0
    .sgpr_count:     108
    .sgpr_spill_count: 325
    .symbol:         _Z14fwd_megakernel6Params.kd
    .uniform_work_group_size: 1
    .uses_dynamic_stack: false
    .vgpr_count:     256
    .vgpr_spill_count: 0
    .wavefront_size: 64
